# k8
# speedup vs baseline: 1.0070x; 1.0070x over previous
; __device__ __forceinline__ unsigned cvtpk(float lo, float hi) { f32x2 v = {lo, hi}; bf16x2_t b = __builtin_convertvector(v, bf16x2_t); return __builtin_bit_cast(unsigned, b); }
; #define XS(s_) (ldbf4(XB + (size_t)(tokbase + (s_)) * D + col) * rsl[(s_) - tb0 + 8])
; __global__ void __launch_bounds__(NTHREADS, 2) mega_fwd(Params p) {
;     ...
;                     int lo = t - hw < 0 ? 0 : t - hw, hi2 = t + hw - 1 > T - 1 ? T - 1 : t + hw - 1;
;                     f32x4 sum = {0.f, 0.f, 0.f, 0.f};
; #pragma unroll
;                     for (int s2 = 0; s2 < 16; ++s2) if (lo + s2 <= hi2) sum += XS(lo + s2);
;                     for (int i = 0; i < 32; ++i) { const float ic = 1.f / (float)(hi2 - lo + 1); const f32x4 o = sum * ic - XS(t);
;                         u32x2 w; w.x = cvtpk(o[0], o[1]); w.y = cvtpk(o[2], o[3]); *(u32x2*)(P + (size_t)(tokbase + t) * D + col) = w;
;                         if (t - hw >= 0) { sum -= XS(t - hw); ++lo; }
;                         if (t + hw <= T - 1) { ++hi2; sum += XS(t + hw); }
;                         ++t; }
.LBB0_621:
	v_add_u32_e32 v42, v22, v19
	v_add_u32_e32 v43, v22, v18
	s_mov_b32 s8, 0xf5a00000
	v_add_co_u32_e32 v38, vcc, s8, v10
	s_nop 1
	v_addc_co_u32_e32 v39, vcc, -1, v11, vcc
	global_load_dwordx2 v[50:51], v[38:39], off
	s_add_i32 s100, s10, 0
	v_add_u32_e32 v40, s100, v23
	v_ashrrev_i32_e32 v41, 31, v40
	v_lshlrev_b64 v[40:41], 11, v[40:41]
	v_lshl_add_u64 v[40:41], v[6:7], 0, v[40:41]
	global_load_dwordx2 v[52:53], v[40:41], off
	v_add_u32_e32 v40, s100, v25
	v_ashrrev_i32_e32 v41, 31, v40
	v_lshlrev_b64 v[40:41], 11, v[40:41]
	v_lshl_add_u64 v[40:41], v[6:7], 0, v[40:41]
	global_load_dwordx2 v[54:55], v[40:41], off
	ds_read_b32 v56, v22
	ds_read_b32 v58, v42
	ds_read_b32 v60, v43
	s_mov_b32 s8, 0xf5a00800
	v_add_co_u32_e32 v38, vcc, s8, v10
	s_nop 1
	v_addc_co_u32_e32 v39, vcc, -1, v11, vcc
	global_load_dwordx2 v[62:63], v[38:39], off
	s_add_i32 s100, s10, 1
	v_add_u32_e32 v40, s100, v23
	v_ashrrev_i32_e32 v41, 31, v40
	v_lshlrev_b64 v[40:41], 11, v[40:41]
	v_lshl_add_u64 v[40:41], v[6:7], 0, v[40:41]
	global_load_dwordx2 v[64:65], v[40:41], off
	v_add_u32_e32 v40, s100, v25
	v_ashrrev_i32_e32 v41, 31, v40
	v_lshlrev_b64 v[40:41], 11, v[40:41]
	v_lshl_add_u64 v[40:41], v[6:7], 0, v[40:41]
	global_load_dwordx2 v[66:67], v[40:41], off
	ds_read_b32 v68, v22 offset:4
	ds_read_b32 v70, v42 offset:4
	ds_read_b32 v72, v43 offset:4
	s_mov_b32 s8, 0xf5a01000
	v_add_co_u32_e32 v38, vcc, s8, v10
	s_nop 1
	v_addc_co_u32_e32 v39, vcc, -1, v11, vcc
	global_load_dwordx2 v[74:75], v[38:39], off
	s_add_i32 s100, s10, 2
	v_add_u32_e32 v40, s100, v23
	v_ashrrev_i32_e32 v41, 31, v40
	v_lshlrev_b64 v[40:41], 11, v[40:41]
	v_lshl_add_u64 v[40:41], v[6:7], 0, v[40:41]
	global_load_dwordx2 v[76:77], v[40:41], off
	v_add_u32_e32 v40, s100, v25
	v_ashrrev_i32_e32 v41, 31, v40
	v_lshlrev_b64 v[40:41], 11, v[40:41]
	v_lshl_add_u64 v[40:41], v[6:7], 0, v[40:41]
	global_load_dwordx2 v[78:79], v[40:41], off
	ds_read_b32 v80, v22 offset:8
	ds_read_b32 v82, v42 offset:8
	ds_read_b32 v84, v43 offset:8
	s_mov_b32 s8, 0xf5a01800
	v_add_co_u32_e32 v38, vcc, s8, v10
	s_nop 1
	v_addc_co_u32_e32 v39, vcc, -1, v11, vcc
	global_load_dwordx2 v[86:87], v[38:39], off
	s_add_i32 s100, s10, 3
	v_add_u32_e32 v40, s100, v23
	v_ashrrev_i32_e32 v41, 31, v40
	v_lshlrev_b64 v[40:41], 11, v[40:41]
	v_lshl_add_u64 v[40:41], v[6:7], 0, v[40:41]
	global_load_dwordx2 v[88:89], v[40:41], off
	v_add_u32_e32 v40, s100, v25
	v_ashrrev_i32_e32 v41, 31, v40
	v_lshlrev_b64 v[40:41], 11, v[40:41]
	v_lshl_add_u64 v[40:41], v[6:7], 0, v[40:41]
	global_load_dwordx2 v[90:91], v[40:41], off
	ds_read_b32 v92, v22 offset:12
	ds_read_b32 v94, v42 offset:12
	ds_read_b32 v96, v43 offset:12
	s_add_i32 s100, s10, 0
	v_add_u32_e32 v27, 1, v26
	v_sub_u32_e32 v30, v27, v21
	v_cvt_f32_i32_e32 v31, v30
	v_add_u32_e32 v36, s100, v0
	v_div_scale_f32 v32, s[8:9], v31, v31, 1.0
	v_rcp_f32_e32 v33, v32
	v_div_scale_f32 v34, vcc, 1.0, v31, 1.0
	v_fma_f32 v35, -v32, v33, 1.0
	v_fmac_f32_e32 v33, v35, v33
	v_mul_f32_e32 v35, v34, v33
	v_fma_f32 v37, -v32, v35, v34
	v_fmac_f32_e32 v35, v37, v33
	v_fma_f32 v32, -v32, v35, v34
	v_div_fmas_f32 v32, v32, v33, v35
	v_div_fixup_f32 v32, v32, v31, 1.0
	v_cmp_lt_i32_e32 vcc, -1, v36
	s_waitcnt vmcnt(11)
	v_lshlrev_b32_e32 v34, 16, v50
	v_and_b32_e32 v35, 0xffff0000, v50
	v_lshlrev_b32_e32 v28, 16, v51
	v_and_b32_e32 v29, 0xffff0000, v51
	s_waitcnt lgkmcnt(11)
	v_pk_mul_f32 v[34:35], v[56:57], v[34:35] op_sel_hi:[0,1]
	v_pk_mul_f32 v[28:29], v[56:57], v[28:29] op_sel_hi:[0,1]
	v_pk_fma_f32 v[28:29], v[4:5], v[32:33], v[28:29] op_sel_hi:[1,0,1] neg_lo:[0,0,1] neg_hi:[0,0,1]
	v_pk_fma_f32 v[30:31], v[2:3], v[32:33], v[34:35] op_sel_hi:[1,0,1] neg_lo:[0,0,1] neg_hi:[0,0,1]
	s_nop 0
	v_cvt_pk_bf16_f32 v30, v30, v31
	v_cvt_pk_bf16_f32 v31, v28, v29
	global_store_dwordx2 v[10:11], v[30:31], off
	s_and_saveexec_b64 s[8:9], vcc
	s_cbranch_execz .Lpool_a0
	v_add_u32_e32 v21, 1, v21
	s_waitcnt vmcnt(11)
	v_lshlrev_b32_e32 v32, 16, v52
	v_and_b32_e32 v33, 0xffff0000, v52
	v_lshlrev_b32_e32 v28, 16, v53
	v_and_b32_e32 v29, 0xffff0000, v53
	s_waitcnt lgkmcnt(10)
	v_pk_fma_f32 v[4:5], v[58:59], v[28:29], v[4:5] op_sel_hi:[0,1,1] neg_lo:[1,0,0] neg_hi:[1,0,0]
	v_pk_fma_f32 v[2:3], v[58:59], v[32:33], v[2:3] op_sel_hi:[0,1,1] neg_lo:[1,0,0] neg_hi:[1,0,0]
.Lpool_a0:
	s_or_b64 exec, exec, s[8:9]
	v_add_u32_e32 v28, s100, v24
	v_cmp_gt_i32_e32 vcc, s59, v28
	s_and_saveexec_b64 s[8:9], vcc
	s_cbranch_execz .Lpool_b0
	s_waitcnt vmcnt(10)
	v_lshlrev_b32_e32 v30, 16, v54
	v_and_b32_e32 v31, 0xffff0000, v54
	v_lshlrev_b32_e32 v28, 16, v55
	v_and_b32_e32 v29, 0xffff0000, v55
	s_waitcnt lgkmcnt(9)
	v_pk_fma_f32 v[4:5], v[60:61], v[28:29], v[4:5] op_sel_hi:[0,1,1]
	v_pk_fma_f32 v[2:3], v[60:61], v[30:31], v[2:3] op_sel_hi:[0,1,1]
	v_mov_b32_e32 v26, v27
.Lpool_b0:
	s_or_b64 exec, exec, s[8:9]
	s_mov_b64 s[8:9], 0x800
	v_lshl_add_u64 v[10:11], v[10:11], 0, s[8:9]
	s_add_i32 s100, s10, 1
	v_add_u32_e32 v27, 1, v26
	v_sub_u32_e32 v30, v27, v21
	v_cvt_f32_i32_e32 v31, v30
	v_add_u32_e32 v36, s100, v0
	v_div_scale_f32 v32, s[8:9], v31, v31, 1.0
	v_rcp_f32_e32 v33, v32
	v_div_scale_f32 v34, vcc, 1.0, v31, 1.0
	v_fma_f32 v35, -v32, v33, 1.0
	v_fmac_f32_e32 v33, v35, v33
	v_mul_f32_e32 v35, v34, v33
	v_fma_f32 v37, -v32, v35, v34
	v_fmac_f32_e32 v35, v37, v33
	v_fma_f32 v32, -v32, v35, v34
	v_div_fmas_f32 v32, v32, v33, v35
	v_div_fixup_f32 v32, v32, v31, 1.0
	v_cmp_lt_i32_e32 vcc, -1, v36
	s_waitcnt vmcnt(9)
	v_lshlrev_b32_e32 v34, 16, v62
	v_and_b32_e32 v35, 0xffff0000, v62
	v_lshlrev_b32_e32 v28, 16, v63
	v_and_b32_e32 v29, 0xffff0000, v63
	s_waitcnt lgkmcnt(8)
	v_pk_mul_f32 v[34:35], v[68:69], v[34:35] op_sel_hi:[0,1]
	v_pk_mul_f32 v[28:29], v[68:69], v[28:29] op_sel_hi:[0,1]
	v_pk_fma_f32 v[28:29], v[4:5], v[32:33], v[28:29] op_sel_hi:[1,0,1] neg_lo:[0,0,1] neg_hi:[0,0,1]
	v_pk_fma_f32 v[30:31], v[2:3], v[32:33], v[34:35] op_sel_hi:[1,0,1] neg_lo:[0,0,1] neg_hi:[0,0,1]
	s_nop 0
	v_cvt_pk_bf16_f32 v30, v30, v31
	v_cvt_pk_bf16_f32 v31, v28, v29
	global_store_dwordx2 v[10:11], v[30:31], off
	s_and_saveexec_b64 s[8:9], vcc
	s_cbranch_execz .Lpool_a1
	v_add_u32_e32 v21, 1, v21
	s_waitcnt vmcnt(9)
	v_lshlrev_b32_e32 v32, 16, v64
	v_and_b32_e32 v33, 0xffff0000, v64
	v_lshlrev_b32_e32 v28, 16, v65
	v_and_b32_e32 v29, 0xffff0000, v65
	s_waitcnt lgkmcnt(7)
	v_pk_fma_f32 v[4:5], v[70:71], v[28:29], v[4:5] op_sel_hi:[0,1,1] neg_lo:[1,0,0] neg_hi:[1,0,0]
	v_pk_fma_f32 v[2:3], v[70:71], v[32:33], v[2:3] op_sel_hi:[0,1,1] neg_lo:[1,0,0] neg_hi:[1,0,0]
; __device__ __forceinline__ unsigned cvtpk(float lo, float hi) { f32x2 v = {lo, hi}; bf16x2_t b = __builtin_convertvector(v, bf16x2_t); return __builtin_bit_cast(unsigned, b); }
; #define XS(s_) (ldbf4(XB + (size_t)(tokbase + (s_)) * D + col) * rsl[(s_) - tb0 + 8])
; __global__ void __launch_bounds__(NTHREADS, 2) mega_fwd(Params p) {
;     ...
;                     for (int i = 0; i < 32; ++i) { const float ic = 1.f / (float)(hi2 - lo + 1); const f32x4 o = sum * ic - XS(t);
;                         u32x2 w; w.x = cvtpk(o[0], o[1]); w.y = cvtpk(o[2], o[3]); *(u32x2*)(P + (size_t)(tokbase + t) * D + col) = w;
;                         if (t - hw >= 0) { sum -= XS(t - hw); ++lo; }
;                         if (t + hw <= T - 1) { ++hi2; sum += XS(t + hw); }
;                         ++t; }
.Lpool_a1:
	s_or_b64 exec, exec, s[8:9]
	v_add_u32_e32 v28, s100, v24
	v_cmp_gt_i32_e32 vcc, s59, v28
	s_and_saveexec_b64 s[8:9], vcc
	s_cbranch_execz .Lpool_b1
	s_waitcnt vmcnt(8)
	v_lshlrev_b32_e32 v30, 16, v66
	v_and_b32_e32 v31, 0xffff0000, v66
	v_lshlrev_b32_e32 v28, 16, v67
	v_and_b32_e32 v29, 0xffff0000, v67
	s_waitcnt lgkmcnt(6)
	v_pk_fma_f32 v[4:5], v[72:73], v[28:29], v[4:5] op_sel_hi:[0,1,1]
	v_pk_fma_f32 v[2:3], v[72:73], v[30:31], v[2:3] op_sel_hi:[0,1,1]
	v_mov_b32_e32 v26, v27
.Lpool_b1:
	s_or_b64 exec, exec, s[8:9]
	s_mov_b64 s[8:9], 0x800
	v_lshl_add_u64 v[10:11], v[10:11], 0, s[8:9]
	s_add_i32 s100, s10, 2
	v_add_u32_e32 v27, 1, v26
	v_sub_u32_e32 v30, v27, v21
	v_cvt_f32_i32_e32 v31, v30
	v_add_u32_e32 v36, s100, v0
	v_div_scale_f32 v32, s[8:9], v31, v31, 1.0
	v_rcp_f32_e32 v33, v32
	v_div_scale_f32 v34, vcc, 1.0, v31, 1.0
	v_fma_f32 v35, -v32, v33, 1.0
	v_fmac_f32_e32 v33, v35, v33
	v_mul_f32_e32 v35, v34, v33
	v_fma_f32 v37, -v32, v35, v34
	v_fmac_f32_e32 v35, v37, v33
	v_fma_f32 v32, -v32, v35, v34
	v_div_fmas_f32 v32, v32, v33, v35
	v_div_fixup_f32 v32, v32, v31, 1.0
	v_cmp_lt_i32_e32 vcc, -1, v36
	s_waitcnt vmcnt(7)
	v_lshlrev_b32_e32 v34, 16, v74
	v_and_b32_e32 v35, 0xffff0000, v74
	v_lshlrev_b32_e32 v28, 16, v75
	v_and_b32_e32 v29, 0xffff0000, v75
	s_waitcnt lgkmcnt(5)
	v_pk_mul_f32 v[34:35], v[80:81], v[34:35] op_sel_hi:[0,1]
	v_pk_mul_f32 v[28:29], v[80:81], v[28:29] op_sel_hi:[0,1]
	v_pk_fma_f32 v[28:29], v[4:5], v[32:33], v[28:29] op_sel_hi:[1,0,1] neg_lo:[0,0,1] neg_hi:[0,0,1]
	v_pk_fma_f32 v[30:31], v[2:3], v[32:33], v[34:35] op_sel_hi:[1,0,1] neg_lo:[0,0,1] neg_hi:[0,0,1]
	s_nop 0
	v_cvt_pk_bf16_f32 v30, v30, v31
	v_cvt_pk_bf16_f32 v31, v28, v29
	global_store_dwordx2 v[10:11], v[30:31], off
	s_and_saveexec_b64 s[8:9], vcc
	s_cbranch_execz .Lpool_a2
	v_add_u32_e32 v21, 1, v21
	s_waitcnt vmcnt(7)
	v_lshlrev_b32_e32 v32, 16, v76
	v_and_b32_e32 v33, 0xffff0000, v76
	v_lshlrev_b32_e32 v28, 16, v77
	v_and_b32_e32 v29, 0xffff0000, v77
	s_waitcnt lgkmcnt(4)
	v_pk_fma_f32 v[4:5], v[82:83], v[28:29], v[4:5] op_sel_hi:[0,1,1] neg_lo:[1,0,0] neg_hi:[1,0,0]
	v_pk_fma_f32 v[2:3], v[82:83], v[32:33], v[2:3] op_sel_hi:[0,1,1] neg_lo:[1,0,0] neg_hi:[1,0,0]
.Lpool_a2:
	s_or_b64 exec, exec, s[8:9]
	v_add_u32_e32 v28, s100, v24
	v_cmp_gt_i32_e32 vcc, s59, v28
	s_and_saveexec_b64 s[8:9], vcc
	s_cbranch_execz .Lpool_b2
	s_waitcnt vmcnt(6)
	v_lshlrev_b32_e32 v30, 16, v78
	v_and_b32_e32 v31, 0xffff0000, v78
	v_lshlrev_b32_e32 v28, 16, v79
	v_and_b32_e32 v29, 0xffff0000, v79
	s_waitcnt lgkmcnt(3)
	v_pk_fma_f32 v[4:5], v[84:85], v[28:29], v[4:5] op_sel_hi:[0,1,1]
	v_pk_fma_f32 v[2:3], v[84:85], v[30:31], v[2:3] op_sel_hi:[0,1,1]
	v_mov_b32_e32 v26, v27
.Lpool_b2:
	s_or_b64 exec, exec, s[8:9]
	s_mov_b64 s[8:9], 0x800
	v_lshl_add_u64 v[10:11], v[10:11], 0, s[8:9]
	s_add_i32 s100, s10, 3
	v_add_u32_e32 v27, 1, v26
	v_sub_u32_e32 v30, v27, v21
	v_cvt_f32_i32_e32 v31, v30
	v_add_u32_e32 v36, s100, v0
	v_div_scale_f32 v32, s[8:9], v31, v31, 1.0
	v_rcp_f32_e32 v33, v32
	v_div_scale_f32 v34, vcc, 1.0, v31, 1.0
	v_fma_f32 v35, -v32, v33, 1.0
	v_fmac_f32_e32 v33, v35, v33
	v_mul_f32_e32 v35, v34, v33
	v_fma_f32 v37, -v32, v35, v34
	v_fmac_f32_e32 v35, v37, v33
	v_fma_f32 v32, -v32, v35, v34
	v_div_fmas_f32 v32, v32, v33, v35
	v_div_fixup_f32 v32, v32, v31, 1.0
	v_cmp_lt_i32_e32 vcc, -1, v36
	s_waitcnt vmcnt(5)
	v_lshlrev_b32_e32 v34, 16, v86
	v_and_b32_e32 v35, 0xffff0000, v86
	v_lshlrev_b32_e32 v28, 16, v87
	v_and_b32_e32 v29, 0xffff0000, v87
	s_waitcnt lgkmcnt(2)
	v_pk_mul_f32 v[34:35], v[92:93], v[34:35] op_sel_hi:[0,1]
	v_pk_mul_f32 v[28:29], v[92:93], v[28:29] op_sel_hi:[0,1]
	v_pk_fma_f32 v[28:29], v[4:5], v[32:33], v[28:29] op_sel_hi:[1,0,1] neg_lo:[0,0,1] neg_hi:[0,0,1]
	v_pk_fma_f32 v[30:31], v[2:3], v[32:33], v[34:35] op_sel_hi:[1,0,1] neg_lo:[0,0,1] neg_hi:[0,0,1]
	s_nop 0
	v_cvt_pk_bf16_f32 v30, v30, v31
	v_cvt_pk_bf16_f32 v31, v28, v29
	global_store_dwordx2 v[10:11], v[30:31], off
	s_and_saveexec_b64 s[8:9], vcc
	s_cbranch_execz .Lpool_a3
	v_add_u32_e32 v21, 1, v21
	s_waitcnt vmcnt(5)
	v_lshlrev_b32_e32 v32, 16, v88
	v_and_b32_e32 v33, 0xffff0000, v88
	v_lshlrev_b32_e32 v28, 16, v89
	v_and_b32_e32 v29, 0xffff0000, v89
	s_waitcnt lgkmcnt(1)
	v_pk_fma_f32 v[4:5], v[94:95], v[28:29], v[4:5] op_sel_hi:[0,1,1] neg_lo:[1,0,0] neg_hi:[1,0,0]
	v_pk_fma_f32 v[2:3], v[94:95], v[32:33], v[2:3] op_sel_hi:[0,1,1] neg_lo:[1,0,0] neg_hi:[1,0,0]
.Lpool_a3:
	s_or_b64 exec, exec, s[8:9]
	v_add_u32_e32 v28, s100, v24
	v_cmp_gt_i32_e32 vcc, s59, v28
	s_and_saveexec_b64 s[8:9], vcc
	s_cbranch_execz .Lpool_b3
	s_waitcnt vmcnt(4)
	v_lshlrev_b32_e32 v30, 16, v90
	v_and_b32_e32 v31, 0xffff0000, v90
	v_lshlrev_b32_e32 v28, 16, v91
	v_and_b32_e32 v29, 0xffff0000, v91
	s_waitcnt lgkmcnt(0)
	v_pk_fma_f32 v[4:5], v[96:97], v[28:29], v[4:5] op_sel_hi:[0,1,1]
	v_pk_fma_f32 v[2:3], v[96:97], v[30:31], v[2:3] op_sel_hi:[0,1,1]
	v_mov_b32_e32 v26, v27
.Lpool_b3:
	s_or_b64 exec, exec, s[8:9]
	s_mov_b64 s[8:9], 0x800
	v_lshl_add_u64 v[10:11], v[10:11], 0, s[8:9]
	s_add_i32 s10, s10, 4
	v_add_u32_e32 v22, 16, v22
	s_cmp_eq_u32 s10, 32
	s_cbranch_scc0 .LBB0_621
	s_branch .LBB0_582

; __device__ __forceinline__ int lane_id_asm() { int l; asm volatile("v_mbcnt_lo_u32_b32 %0, -1, 0\n\tv_mbcnt_hi_u32_b32 %0, -1, %0" : "=v"(l)); return l; }
; __device__ __forceinline__ float sum32(float v) { auto rr = __builtin_amdgcn_permlane32_swap(__float_as_uint(v), __float_as_uint(v), false, false); return __uint_as_float(rr[0]) + __uint_as_float(rr[1]); }
; __global__ void __launch_bounds__(NTHREADS, 2) mega_fwd(Params p) {
;     ...
;                     const float ia = __builtin_amdgcn_rcpf(la_[0]), ib = lam * __builtin_amdgcn_rcpf(lb_[0]); float ss = 0.f;
;                     const int l3 = lane_id_asm(), hi2 = l3 >> 5;
;                     bf16_t* orow = Ob + (size_t)(b * T + qb * 256 + wave * 32 + (l3 & 31)) * 1024 + h * 128;
; #pragma unroll
;                     for (int db = 0; db < 4; ++db)
; #pragma unroll
;                         for (int r = 0; r < 16; ++r) { const float v = oa[db][r] * ia - ob[db][r] * ib; oa[db][r] = v; ss += v * v; }
;                     ss = sum32(ss);
;                     const float rinv = rsqrtf(ss * (1.f / 128.f) + EPS) * (1.f - LAM_INIT2);
;     ...
;                         for (int g4 = 0; g4 < 4; ++g4) { const int d = db * 32 + g4 * 8 + hi2 * 4; const f32x4 gv = *(const f32x4*)(sg + d); u32x2 w;
.LBB0_1323:
	v_add_f32_e32 v2, v228, v3
	v_rcp_f32_e32 v2, v2
	v_rcp_f32_e32 v0, v0
	v_mbcnt_lo_u32_b32 v4, -1, 0
	v_mbcnt_hi_u32_b32 v4, -1, v4
	s_add_i32 s83, s83, s52
	v_mul_f32_e32 v144, s48, v2
	v_and_or_b32 v2, v4, 31, s43
	v_ashrrev_i32_e32 v3, 31, v2
	v_lshlrev_b64 v[2:3], 11, v[2:3]
	v_lshl_add_u64 v[2:3], s[40:41], 0, v[2:3]
	s_mov_b32 s43, s17
	v_pk_mul_f32 v[12:13], v[144:145], v[82:83] op_sel_hi:[0,1]
	v_lshl_add_u64 v[8:9], v[2:3], 0, s[42:43]
	v_ashrrev_i32_e32 v2, 3, v4
	v_pk_fma_f32 v[146:147], v[0:1], v[18:19], v[12:13] op_sel_hi:[0,1,1] neg_lo:[0,0,1] neg_hi:[0,0,1]
	v_pk_mul_f32 v[12:13], v[144:145], v[80:81] op_sel_hi:[0,1]
	v_and_b32_e32 v10, -4, v2
	v_pk_fma_f32 v[148:149], v[0:1], v[16:17], v[12:13] op_sel_hi:[0,1,1] neg_lo:[0,0,1] neg_hi:[0,0,1]
	v_ashrrev_i32_e32 v11, 31, v10
	v_mul_f32_e32 v12, v149, v149
	v_lshl_add_u64 v[6:7], v[10:11], 2, s[36:37]
	global_load_dwordx4 v[160:163], v[6:7], off
	global_load_dwordx4 v[164:167], v[6:7], off offset:32
	global_load_dwordx4 v[168:171], v[6:7], off offset:64
	global_load_dwordx4 v[172:175], v[6:7], off offset:96
	global_load_dwordx4 v[176:179], v[6:7], off offset:128
	global_load_dwordx4 v[180:183], v[6:7], off offset:160
	global_load_dwordx4 v[184:187], v[6:7], off offset:192
	global_load_dwordx4 v[188:191], v[6:7], off offset:224
	global_load_dwordx4 v[192:195], v[6:7], off offset:256
	global_load_dwordx4 v[196:199], v[6:7], off offset:288
	global_load_dwordx4 v[200:203], v[6:7], off offset:320
	global_load_dwordx4 v[204:207], v[6:7], off offset:352
	global_load_dwordx4 v[216:219], v[6:7], off offset:384
	global_load_dwordx4 v[220:223], v[6:7], off offset:416
	global_load_dwordx4 v[238:241], v[6:7], off offset:448
	global_load_dwordx4 v[242:245], v[6:7], off offset:480
	v_pk_fma_f32 v[12:13], v[148:149], v[148:149], v[12:13] op_sel_hi:[1,1,0]
	v_lshl_add_u64 v[8:9], v[10:11], 1, v[8:9]
	v_pk_mul_f32 v[10:11], v[144:145], v[86:87] op_sel_hi:[0,1]
	v_pk_fma_f32 v[12:13], v[146:147], v[146:147], v[12:13]
	v_mul_f32_e32 v14, v147, v147
	v_pk_fma_f32 v[150:151], v[0:1], v[22:23], v[10:11] op_sel_hi:[0,1,1] neg_lo:[0,0,1] neg_hi:[0,0,1]
	v_pk_mul_f32 v[10:11], v[144:145], v[84:85] op_sel_hi:[0,1]
	v_pk_add_f32 v[12:13], v[12:13], v[14:15] op_sel_hi:[1,0]
	v_pk_fma_f32 v[152:153], v[0:1], v[20:21], v[10:11] op_sel_hi:[0,1,1] neg_lo:[0,0,1] neg_hi:[0,0,1]
	v_pk_fma_f32 v[10:11], v[152:153], v[152:153], v[12:13]
	v_mul_f32_e32 v12, v153, v153
	v_pk_add_f32 v[10:11], v[10:11], v[12:13] op_sel_hi:[1,0]
	v_mul_f32_e32 v12, v151, v151
	v_pk_fma_f32 v[10:11], v[150:151], v[150:151], v[10:11]
	v_pk_add_f32 v[10:11], v[10:11], v[12:13] op_sel_hi:[1,0]
	v_pk_mul_f32 v[12:13], v[144:145], v[90:91] op_sel_hi:[0,1]
	v_pk_fma_f32 v[90:91], v[0:1], v[26:27], v[12:13] op_sel_hi:[0,1,1] neg_lo:[0,0,1] neg_hi:[0,0,1]
	v_pk_mul_f32 v[12:13], v[144:145], v[88:89] op_sel_hi:[0,1]
	v_pk_fma_f32 v[154:155], v[0:1], v[24:25], v[12:13] op_sel_hi:[0,1,1] neg_lo:[0,0,1] neg_hi:[0,0,1]
	v_pk_fma_f32 v[10:11], v[154:155], v[154:155], v[10:11]
	v_mul_f32_e32 v12, v155, v155
	v_pk_add_f32 v[10:11], v[10:11], v[12:13] op_sel_hi:[1,0]
	v_mul_f32_e32 v12, v91, v91
	v_pk_fma_f32 v[10:11], v[90:91], v[90:91], v[10:11]
	v_pk_mul_f32 v[16:17], v[144:145], v[104:105] op_sel_hi:[0,1]
	v_pk_add_f32 v[10:11], v[10:11], v[12:13] op_sel_hi:[1,0]
	v_pk_mul_f32 v[12:13], v[144:145], v[94:95] op_sel_hi:[0,1]
	v_pk_fma_f32 v[86:87], v[0:1], v[30:31], v[12:13] op_sel_hi:[0,1,1] neg_lo:[0,0,1] neg_hi:[0,0,1]
	v_pk_mul_f32 v[12:13], v[144:145], v[92:93] op_sel_hi:[0,1]
	v_pk_fma_f32 v[92:93], v[0:1], v[28:29], v[12:13] op_sel_hi:[0,1,1] neg_lo:[0,0,1] neg_hi:[0,0,1]
	v_pk_fma_f32 v[10:11], v[92:93], v[92:93], v[10:11]
	v_mul_f32_e32 v12, v93, v93
	v_pk_add_f32 v[10:11], v[10:11], v[12:13] op_sel_hi:[1,0]
	v_mul_f32_e32 v12, v87, v87
	v_pk_fma_f32 v[10:11], v[86:87], v[86:87], v[10:11]
	v_pk_fma_f32 v[18:19], v[0:1], v[40:41], v[16:17] op_sel_hi:[0,1,1] neg_lo:[0,0,1] neg_hi:[0,0,1]
	v_pk_add_f32 v[10:11], v[10:11], v[12:13] op_sel_hi:[1,0]
	v_pk_mul_f32 v[12:13], v[144:145], v[130:131] op_sel_hi:[0,1]
	v_pk_fma_f32 v[82:83], v[0:1], v[66:67], v[12:13] op_sel_hi:[0,1,1] neg_lo:[0,0,1] neg_hi:[0,0,1]
	v_pk_mul_f32 v[12:13], v[144:145], v[128:129] op_sel_hi:[0,1]
	v_pk_fma_f32 v[88:89], v[0:1], v[64:65], v[12:13] op_sel_hi:[0,1,1] neg_lo:[0,0,1] neg_hi:[0,0,1]
	v_pk_fma_f32 v[10:11], v[88:89], v[88:89], v[10:11]
	v_mul_f32_e32 v12, v89, v89
	v_pk_add_f32 v[10:11], v[10:11], v[12:13] op_sel_hi:[1,0]
	v_mul_f32_e32 v12, v83, v83
	v_pk_fma_f32 v[10:11], v[82:83], v[82:83], v[10:11]
	v_mul_f32_e32 v16, v19, v19
	v_pk_add_f32 v[10:11], v[10:11], v[12:13] op_sel_hi:[1,0]
	v_pk_mul_f32 v[12:13], v[144:145], v[134:135] op_sel_hi:[0,1]
	v_pk_fma_f32 v[80:81], v[0:1], v[70:71], v[12:13] op_sel_hi:[0,1,1] neg_lo:[0,0,1] neg_hi:[0,0,1]
	v_pk_mul_f32 v[12:13], v[144:145], v[132:133] op_sel_hi:[0,1]
	v_pk_fma_f32 v[84:85], v[0:1], v[68:69], v[12:13] op_sel_hi:[0,1,1] neg_lo:[0,0,1] neg_hi:[0,0,1]
	v_pk_fma_f32 v[10:11], v[84:85], v[84:85], v[10:11]
	v_mul_f32_e32 v12, v85, v85
	v_pk_add_f32 v[10:11], v[10:11], v[12:13] op_sel_hi:[1,0]
	v_mul_f32_e32 v12, v81, v81
	v_pk_fma_f32 v[10:11], v[80:81], v[80:81], v[10:11]
	s_cmpk_gt_i32 s83, 0x9ff
	v_pk_add_f32 v[10:11], v[10:11], v[12:13] op_sel_hi:[1,0]
	v_pk_mul_f32 v[12:13], v[144:145], v[138:139] op_sel_hi:[0,1]
	v_pk_fma_f32 v[70:71], v[0:1], v[74:75], v[12:13] op_sel_hi:[0,1,1] neg_lo:[0,0,1] neg_hi:[0,0,1]
	v_pk_mul_f32 v[12:13], v[144:145], v[136:137] op_sel_hi:[0,1]
	v_pk_fma_f32 v[74:75], v[0:1], v[72:73], v[12:13] op_sel_hi:[0,1,1] neg_lo:[0,0,1] neg_hi:[0,0,1]
; __device__ __forceinline__ float sum32(float v) { auto rr = __builtin_amdgcn_permlane32_swap(__float_as_uint(v), __float_as_uint(v), false, false); return __uint_as_float(rr[0]) + __uint_as_float(rr[1]); }
; __global__ void __launch_bounds__(NTHREADS, 2) mega_fwd(Params p) {
;     ...
;                         for (int r = 0; r < 16; ++r) { const float v = oa[db][r] * ia - ob[db][r] * ib; oa[db][r] = v; ss += v * v; }
;                     ss = sum32(ss);
;                     const float rinv = rsqrtf(ss * (1.f / 128.f) + EPS) * (1.f - LAM_INIT2);
	v_pk_fma_f32 v[10:11], v[74:75], v[74:75], v[10:11]
	v_mul_f32_e32 v12, v75, v75
	v_pk_add_f32 v[10:11], v[10:11], v[12:13] op_sel_hi:[1,0]
	v_mul_f32_e32 v12, v71, v71
	v_pk_fma_f32 v[10:11], v[70:71], v[70:71], v[10:11]
	s_nop 0
	v_pk_add_f32 v[10:11], v[10:11], v[12:13] op_sel_hi:[1,0]
	v_pk_mul_f32 v[12:13], v[144:145], v[142:143] op_sel_hi:[0,1]
	v_pk_fma_f32 v[66:67], v[0:1], v[78:79], v[12:13] op_sel_hi:[0,1,1] neg_lo:[0,0,1] neg_hi:[0,0,1]
	v_pk_mul_f32 v[12:13], v[144:145], v[140:141] op_sel_hi:[0,1]
	v_pk_fma_f32 v[72:73], v[0:1], v[76:77], v[12:13] op_sel_hi:[0,1,1] neg_lo:[0,0,1] neg_hi:[0,0,1]
	v_pk_fma_f32 v[10:11], v[72:73], v[72:73], v[10:11]
	v_mul_f32_e32 v12, v73, v73
	v_pk_add_f32 v[10:11], v[10:11], v[12:13] op_sel_hi:[1,0]
	v_mul_f32_e32 v12, v67, v67
	v_pk_fma_f32 v[10:11], v[66:67], v[66:67], v[10:11]
	s_nop 0
	v_pk_add_f32 v[10:11], v[10:11], v[12:13] op_sel_hi:[1,0]
	v_pk_mul_f32 v[12:13], v[144:145], v[114:115] op_sel_hi:[0,1]
	v_pk_fma_f32 v[64:65], v[0:1], v[50:51], v[12:13] op_sel_hi:[0,1,1] neg_lo:[0,0,1] neg_hi:[0,0,1]
	v_pk_mul_f32 v[12:13], v[144:145], v[112:113] op_sel_hi:[0,1]
	v_pk_fma_f32 v[68:69], v[0:1], v[48:49], v[12:13] op_sel_hi:[0,1,1] neg_lo:[0,0,1] neg_hi:[0,0,1]
	v_pk_fma_f32 v[10:11], v[68:69], v[68:69], v[10:11]
	v_mul_f32_e32 v12, v69, v69
	v_pk_add_f32 v[10:11], v[10:11], v[12:13] op_sel_hi:[1,0]
	v_mul_f32_e32 v12, v65, v65
	v_pk_fma_f32 v[10:11], v[64:65], v[64:65], v[10:11]
	s_nop 0
	v_pk_add_f32 v[10:11], v[10:11], v[12:13] op_sel_hi:[1,0]
	v_pk_mul_f32 v[12:13], v[144:145], v[118:119] op_sel_hi:[0,1]
	v_pk_fma_f32 v[30:31], v[0:1], v[54:55], v[12:13] op_sel_hi:[0,1,1] neg_lo:[0,0,1] neg_hi:[0,0,1]
	v_pk_mul_f32 v[12:13], v[144:145], v[116:117] op_sel_hi:[0,1]
	v_pk_fma_f32 v[52:53], v[0:1], v[52:53], v[12:13] op_sel_hi:[0,1,1] neg_lo:[0,0,1] neg_hi:[0,0,1]
	v_pk_fma_f32 v[10:11], v[52:53], v[52:53], v[10:11]
	v_mul_f32_e32 v12, v53, v53
	v_pk_add_f32 v[10:11], v[10:11], v[12:13] op_sel_hi:[1,0]
	v_mul_f32_e32 v12, v31, v31
	v_pk_fma_f32 v[10:11], v[30:31], v[30:31], v[10:11]
	s_nop 0
	v_pk_add_f32 v[10:11], v[10:11], v[12:13] op_sel_hi:[1,0]
	v_pk_mul_f32 v[12:13], v[144:145], v[122:123] op_sel_hi:[0,1]
	v_pk_fma_f32 v[28:29], v[0:1], v[58:59], v[12:13] op_sel_hi:[0,1,1] neg_lo:[0,0,1] neg_hi:[0,0,1]
	v_pk_mul_f32 v[12:13], v[144:145], v[120:121] op_sel_hi:[0,1]
	v_pk_fma_f32 v[50:51], v[0:1], v[56:57], v[12:13] op_sel_hi:[0,1,1] neg_lo:[0,0,1] neg_hi:[0,0,1]
	v_pk_fma_f32 v[10:11], v[50:51], v[50:51], v[10:11]
	v_mul_f32_e32 v12, v51, v51
	v_pk_add_f32 v[10:11], v[10:11], v[12:13] op_sel_hi:[1,0]
	v_mul_f32_e32 v12, v29, v29
	v_pk_fma_f32 v[10:11], v[28:29], v[28:29], v[10:11]
	s_nop 0
	v_pk_add_f32 v[10:11], v[10:11], v[12:13] op_sel_hi:[1,0]
	v_pk_mul_f32 v[12:13], v[144:145], v[126:127] op_sel_hi:[0,1]
	v_pk_fma_f32 v[24:25], v[0:1], v[62:63], v[12:13] op_sel_hi:[0,1,1] neg_lo:[0,0,1] neg_hi:[0,0,1]
	v_pk_mul_f32 v[12:13], v[144:145], v[124:125] op_sel_hi:[0,1]
	v_pk_fma_f32 v[48:49], v[0:1], v[60:61], v[12:13] op_sel_hi:[0,1,1] neg_lo:[0,0,1] neg_hi:[0,0,1]
	v_pk_fma_f32 v[10:11], v[48:49], v[48:49], v[10:11]
	v_mul_f32_e32 v12, v49, v49
	v_pk_add_f32 v[10:11], v[10:11], v[12:13] op_sel_hi:[1,0]
	v_mul_f32_e32 v12, v25, v25
	v_pk_fma_f32 v[10:11], v[24:25], v[24:25], v[10:11]
	s_nop 0
	v_pk_add_f32 v[10:11], v[10:11], v[12:13] op_sel_hi:[1,0]
	v_pk_mul_f32 v[12:13], v[144:145], v[98:99] op_sel_hi:[0,1]
	v_pk_fma_f32 v[20:21], v[0:1], v[34:35], v[12:13] op_sel_hi:[0,1,1] neg_lo:[0,0,1] neg_hi:[0,0,1]
	v_pk_mul_f32 v[12:13], v[144:145], v[96:97] op_sel_hi:[0,1]
	v_pk_fma_f32 v[26:27], v[0:1], v[32:33], v[12:13] op_sel_hi:[0,1,1] neg_lo:[0,0,1] neg_hi:[0,0,1]
	v_pk_fma_f32 v[10:11], v[26:27], v[26:27], v[10:11]
	v_mul_f32_e32 v12, v27, v27
	v_pk_add_f32 v[10:11], v[10:11], v[12:13] op_sel_hi:[1,0]
	v_mul_f32_e32 v12, v21, v21
	v_pk_fma_f32 v[10:11], v[20:21], v[20:21], v[10:11]
	s_nop 0
	v_pk_add_f32 v[10:11], v[10:11], v[12:13] op_sel_hi:[1,0]
	v_pk_mul_f32 v[12:13], v[144:145], v[102:103] op_sel_hi:[0,1]
	v_pk_fma_f32 v[14:15], v[0:1], v[38:39], v[12:13] op_sel_hi:[0,1,1] neg_lo:[0,0,1] neg_hi:[0,0,1]
	v_pk_mul_f32 v[12:13], v[144:145], v[100:101] op_sel_hi:[0,1]
	v_pk_fma_f32 v[22:23], v[0:1], v[36:37], v[12:13] op_sel_hi:[0,1,1] neg_lo:[0,0,1] neg_hi:[0,0,1]
	v_pk_fma_f32 v[10:11], v[22:23], v[22:23], v[10:11]
	v_mul_f32_e32 v12, v23, v23
	v_pk_add_f32 v[10:11], v[10:11], v[12:13] op_sel_hi:[1,0]
	v_mul_f32_e32 v12, v15, v15
	v_pk_fma_f32 v[10:11], v[14:15], v[14:15], v[10:11]
	s_nop 0
	v_pk_add_f32 v[12:13], v[10:11], v[12:13] op_sel_hi:[1,0]
	v_pk_mul_f32 v[10:11], v[144:145], v[106:107] op_sel_hi:[0,1]
	v_pk_fma_f32 v[12:13], v[18:19], v[18:19], v[12:13]
	v_pk_fma_f32 v[10:11], v[0:1], v[42:43], v[10:11] op_sel_hi:[0,1,1] neg_lo:[0,0,1] neg_hi:[0,0,1]
	v_pk_add_f32 v[12:13], v[12:13], v[16:17] op_sel_hi:[1,0]
	v_mul_f32_e32 v16, v11, v11
	v_pk_fma_f32 v[12:13], v[10:11], v[10:11], v[12:13]
	s_nop 0
	v_pk_add_f32 v[32:33], v[12:13], v[16:17] op_sel_hi:[1,0]
	v_pk_mul_f32 v[16:17], v[144:145], v[108:109] op_sel_hi:[0,1]
	v_pk_mul_f32 v[12:13], v[144:145], v[110:111] op_sel_hi:[0,1]
	v_pk_fma_f32 v[16:17], v[0:1], v[44:45], v[16:17] op_sel_hi:[0,1,1] neg_lo:[0,0,1] neg_hi:[0,0,1]
	v_pk_fma_f32 v[12:13], v[0:1], v[46:47], v[12:13] op_sel_hi:[0,1,1] neg_lo:[0,0,1] neg_hi:[0,0,1]
	v_pk_fma_f32 v[32:33], v[16:17], v[16:17], v[32:33]
	v_mul_f32_e32 v0, v17, v17
	v_pk_add_f32 v[32:33], v[32:33], v[0:1] op_sel_hi:[1,0]
	v_mul_f32_e32 v0, v13, v13
	v_pk_fma_f32 v[32:33], v[12:13], v[12:13], v[32:33]
	s_nop 0
	v_pk_add_f32 v[32:33], v[32:33], v[0:1] op_sel_hi:[1,0]
	s_nop 0
	v_mov_b32_e32 v0, v32
	s_nop 1
	v_permlane32_swap_b32_e32 v32, v0
	v_add_f32_e32 v0, v32, v0
	v_fmamk_f32 v0, v0, 0x3c000000, v254
	v_cmp_gt_f32_e32 vcc, s56, v0
	v_mul_f32_e32 v32, 0x4b800000, v0
	s_nop 0
	v_cndmask_b32_e32 v0, v0, v32, vcc
	v_rsq_f32_e32 v0, v0
	s_nop 0
	v_mul_f32_e32 v32, 0x45800000, v0
	v_cndmask_b32_e32 v0, v0, v32, vcc
	v_mul_f32_e32 v0, 0x3f077f5a, v0
	v_pk_mul_f32 v[32:33], v[0:1], v[148:149] op_sel_hi:[0,1]
	s_waitcnt vmcnt(15)
; __device__ __forceinline__ unsigned cvtpk(float lo, float hi) { f32x2 v = {lo, hi}; bf16x2_t b = __builtin_convertvector(v, bf16x2_t); return __builtin_bit_cast(unsigned, b); }
; __global__ void __launch_bounds__(NTHREADS, 2) mega_fwd(Params p) {
;     ...
;                     for (int db = 0; db < 4; ++db)
; #pragma unroll
;                         for (int g4 = 0; g4 < 4; ++g4) { const int d = db * 32 + g4 * 8 + hi2 * 4; const f32x4 gv = *(const f32x4*)(sg + d); u32x2 w;
;                             w.x = cvtpk(oa[db][4 * g4] * rinv * gv.x, oa[db][4 * g4 + 1] * rinv * gv.y); w.y = cvtpk(oa[db][4 * g4 + 2] * rinv * gv.z, oa[db][4 * g4 + 3] * rinv * gv.w);
;                             *(u32x2*)(orow + d) = w; }
	v_pk_mul_f32 v[2:3], v[160:161], v[32:33]
	v_pk_mul_f32 v[32:33], v[0:1], v[146:147] op_sel_hi:[0,1]
	v_pk_mul_f32 v[4:5], v[162:163], v[32:33]
	v_cvt_pk_bf16_f32 v2, v2, v3
	v_cvt_pk_bf16_f32 v3, v4, v5
	global_store_dwordx2 v[8:9], v[2:3], off
	v_pk_mul_f32 v[32:33], v[0:1], v[152:153] op_sel_hi:[0,1]
	v_pk_mul_f32 v[30:31], v[0:1], v[30:31] op_sel_hi:[0,1]
	v_pk_mul_f32 v[28:29], v[0:1], v[28:29] op_sel_hi:[0,1]
	v_pk_mul_f32 v[24:25], v[0:1], v[24:25] op_sel_hi:[0,1]
	v_pk_mul_f32 v[20:21], v[0:1], v[20:21] op_sel_hi:[0,1]
	v_pk_mul_f32 v[14:15], v[0:1], v[14:15] op_sel_hi:[0,1]
	v_pk_mul_f32 v[10:11], v[0:1], v[10:11] op_sel_hi:[0,1]
	s_waitcnt vmcnt(15)
	v_pk_mul_f32 v[2:3], v[164:165], v[32:33]
	v_pk_mul_f32 v[32:33], v[0:1], v[150:151] op_sel_hi:[0,1]
	v_pk_mul_f32 v[4:5], v[166:167], v[32:33]
	v_cvt_pk_bf16_f32 v2, v2, v3
	v_cvt_pk_bf16_f32 v3, v4, v5
	global_store_dwordx2 v[8:9], v[2:3], off offset:16
	v_pk_mul_f32 v[32:33], v[0:1], v[154:155] op_sel_hi:[0,1]
	s_waitcnt vmcnt(15)
	v_pk_mul_f32 v[2:3], v[168:169], v[32:33]
	v_pk_mul_f32 v[32:33], v[0:1], v[90:91] op_sel_hi:[0,1]
	v_pk_mul_f32 v[4:5], v[170:171], v[32:33]
	v_cvt_pk_bf16_f32 v2, v2, v3
	v_cvt_pk_bf16_f32 v3, v4, v5
	global_store_dwordx2 v[8:9], v[2:3], off offset:32
	v_pk_mul_f32 v[32:33], v[0:1], v[92:93] op_sel_hi:[0,1]
	s_waitcnt vmcnt(15)
	v_pk_mul_f32 v[2:3], v[172:173], v[32:33]
	v_pk_mul_f32 v[32:33], v[0:1], v[86:87] op_sel_hi:[0,1]
	v_pk_mul_f32 v[4:5], v[174:175], v[32:33]
	v_cvt_pk_bf16_f32 v2, v2, v3
	v_cvt_pk_bf16_f32 v3, v4, v5
	global_store_dwordx2 v[8:9], v[2:3], off offset:48
	v_pk_mul_f32 v[32:33], v[0:1], v[88:89] op_sel_hi:[0,1]
	s_waitcnt vmcnt(15)
	v_pk_mul_f32 v[2:3], v[176:177], v[32:33]
	v_pk_mul_f32 v[32:33], v[0:1], v[82:83] op_sel_hi:[0,1]
	v_pk_mul_f32 v[4:5], v[178:179], v[32:33]
	v_cvt_pk_bf16_f32 v2, v2, v3
	v_cvt_pk_bf16_f32 v3, v4, v5
	global_store_dwordx2 v[8:9], v[2:3], off offset:64
	v_pk_mul_f32 v[32:33], v[0:1], v[84:85] op_sel_hi:[0,1]
	s_waitcnt vmcnt(15)
	v_pk_mul_f32 v[2:3], v[180:181], v[32:33]
	v_pk_mul_f32 v[32:33], v[0:1], v[80:81] op_sel_hi:[0,1]
	v_pk_mul_f32 v[4:5], v[182:183], v[32:33]
	v_cvt_pk_bf16_f32 v2, v2, v3
	v_cvt_pk_bf16_f32 v3, v4, v5
	global_store_dwordx2 v[8:9], v[2:3], off offset:80
	v_pk_mul_f32 v[32:33], v[0:1], v[74:75] op_sel_hi:[0,1]
	s_waitcnt vmcnt(15)
	v_pk_mul_f32 v[2:3], v[184:185], v[32:33]
	v_pk_mul_f32 v[32:33], v[0:1], v[70:71] op_sel_hi:[0,1]
	v_pk_mul_f32 v[4:5], v[186:187], v[32:33]
	v_cvt_pk_bf16_f32 v2, v2, v3
	v_cvt_pk_bf16_f32 v3, v4, v5
	global_store_dwordx2 v[8:9], v[2:3], off offset:96
	v_pk_mul_f32 v[32:33], v[0:1], v[72:73] op_sel_hi:[0,1]
	s_waitcnt vmcnt(15)
	v_pk_mul_f32 v[2:3], v[188:189], v[32:33]
	v_pk_mul_f32 v[32:33], v[0:1], v[66:67] op_sel_hi:[0,1]
	v_pk_mul_f32 v[4:5], v[190:191], v[32:33]
	v_cvt_pk_bf16_f32 v2, v2, v3
	v_cvt_pk_bf16_f32 v3, v4, v5
	global_store_dwordx2 v[8:9], v[2:3], off offset:112
	v_pk_mul_f32 v[32:33], v[0:1], v[68:69] op_sel_hi:[0,1]
	s_waitcnt vmcnt(15)
	v_pk_mul_f32 v[2:3], v[192:193], v[32:33]
	v_pk_mul_f32 v[32:33], v[0:1], v[64:65] op_sel_hi:[0,1]
	v_pk_mul_f32 v[4:5], v[194:195], v[32:33]
	v_cvt_pk_bf16_f32 v2, v2, v3
	v_cvt_pk_bf16_f32 v3, v4, v5
	global_store_dwordx2 v[8:9], v[2:3], off offset:128
	v_pk_mul_f32 v[32:33], v[0:1], v[52:53] op_sel_hi:[0,1]
	s_waitcnt vmcnt(15)
	v_pk_mul_f32 v[2:3], v[196:197], v[32:33]
	v_pk_mul_f32 v[4:5], v[198:199], v[30:31]
	v_cvt_pk_bf16_f32 v2, v2, v3
	v_cvt_pk_bf16_f32 v3, v4, v5
	global_store_dwordx2 v[8:9], v[2:3], off offset:144
	v_pk_mul_f32 v[30:31], v[0:1], v[50:51] op_sel_hi:[0,1]
	s_waitcnt vmcnt(15)
	v_pk_mul_f32 v[2:3], v[200:201], v[30:31]
	v_pk_mul_f32 v[4:5], v[202:203], v[28:29]
	v_cvt_pk_bf16_f32 v2, v2, v3
	v_cvt_pk_bf16_f32 v3, v4, v5
	global_store_dwordx2 v[8:9], v[2:3], off offset:160
	v_pk_mul_f32 v[28:29], v[0:1], v[48:49] op_sel_hi:[0,1]
	s_waitcnt vmcnt(15)
	v_pk_mul_f32 v[2:3], v[204:205], v[28:29]
	v_pk_mul_f32 v[4:5], v[206:207], v[24:25]
	v_cvt_pk_bf16_f32 v2, v2, v3
	v_cvt_pk_bf16_f32 v3, v4, v5
	global_store_dwordx2 v[8:9], v[2:3], off offset:176
	v_pk_mul_f32 v[24:25], v[0:1], v[26:27] op_sel_hi:[0,1]
	s_waitcnt vmcnt(15)
	v_pk_mul_f32 v[2:3], v[216:217], v[24:25]
	v_pk_mul_f32 v[4:5], v[218:219], v[20:21]
	v_cvt_pk_bf16_f32 v2, v2, v3
	v_cvt_pk_bf16_f32 v3, v4, v5
	global_store_dwordx2 v[8:9], v[2:3], off offset:192
	v_pk_mul_f32 v[20:21], v[0:1], v[22:23] op_sel_hi:[0,1]
	s_waitcnt vmcnt(15)
	v_pk_mul_f32 v[2:3], v[220:221], v[20:21]
	v_pk_mul_f32 v[4:5], v[222:223], v[14:15]
	v_cvt_pk_bf16_f32 v2, v2, v3
	v_cvt_pk_bf16_f32 v3, v4, v5
	global_store_dwordx2 v[8:9], v[2:3], off offset:208
	v_pk_mul_f32 v[14:15], v[0:1], v[18:19] op_sel_hi:[0,1]
	s_waitcnt vmcnt(15)
	v_pk_mul_f32 v[2:3], v[238:239], v[14:15]
	v_pk_mul_f32 v[4:5], v[240:241], v[10:11]
	v_cvt_pk_bf16_f32 v2, v2, v3
	v_cvt_pk_bf16_f32 v3, v4, v5
	global_store_dwordx2 v[8:9], v[2:3], off offset:224
	v_pk_mul_f32 v[6:7], v[0:1], v[16:17] op_sel_hi:[0,1]
	s_waitcnt vmcnt(15)
	v_pk_mul_f32 v[2:3], v[242:243], v[6:7]
	v_pk_mul_f32 v[6:7], v[0:1], v[12:13] op_sel_hi:[0,1]
	v_pk_mul_f32 v[4:5], v[244:245], v[6:7]
	v_cvt_pk_bf16_f32 v2, v2, v3
	v_cvt_pk_bf16_f32 v3, v4, v5
	global_store_dwordx2 v[8:9], v[2:3], off offset:240
	s_cbranch_scc1 .LBB0_1413
